# D/F epilogue rowsum4: ds_bpermute round trips replaced by v_permlane16_swap / v_permlane32_swap register exchanges
# baseline (speedup 1.0000x reference)
.LBB0_1445:
	s_lshl_b32 s4, s24, 3
	s_and_b32 s14, s4, -16
	v_mov_b32_e32 v14, v220
	v_mov_b32_e32 v94, v219
	s_add_i32 s13, s14, 0x4000
	s_lshl_b32 s4, s26, 8
	s_lshl_b32 s10, s24, 7
	v_readlane_b32 s11, v251, 22
	s_and_b32 s10, s10, 0x80
	v_add_u32_e32 v92, s13, v14
	s_add_i32 s15, s4, s11
	v_ashrrev_i32_e32 v93, 31, v92
	s_add_i32 s15, s15, s10
	s_ashr_i32 s10, s24, 5
	v_lshlrev_b64 v[92:93], 11, v[92:93]
	s_mov_b64 s[62:63], s[68:69]
	v_lshl_add_u32 v94, v94, 3, s15
	v_or_b32_e32 v194, s4, v224
	s_ashr_i32 s11, s10, 31
	s_mul_i32 s18, s10, 0x6000
	v_readlane_b32 s38, v250, 45
	v_lshl_add_u64 v[92:93], s[62:63], 0, v[92:93]
	v_ashrrev_i32_e32 v95, 31, v94
	s_mul_hi_i32 s4, s10, 0x6000
	v_readlane_b32 s39, v250, 46
	s_add_u32 s38, s38, s18
	v_ashrrev_i32_e32 v195, 31, v194
	v_lshl_add_u64 v[92:93], v[94:95], 1, v[92:93]
	s_addc_u32 s39, s39, s4
	v_lshlrev_b64 v[94:95], 2, v[194:195]
	s_mov_b64 s[76:77], s[2:3]
	s_lshl_b64 s[10:11], s[10:11], 12
	s_mov_b64 s[2:3], s[8:9]
	v_lshl_add_u64 v[96:97], s[38:39], 0, v[94:95]
	s_add_u32 s38, s2, s10
	s_addc_u32 s39, s3, s11
	v_lshl_add_u64 v[98:99], s[76:77], 0, v[94:95]
	v_lshl_add_u64 v[116:117], s[38:39], 0, v[94:95]
	v_lshl_add_u64 v[98:99], v[98:99], 0, s[10:11]
	global_load_dwordx2 v[192:193], v[92:93], off
	global_load_dwordx4 v[132:135], v[96:97], off
	global_load_dwordx4 v[144:147], v[116:117], off
	global_load_dwordx4 v[104:107], v[96:97], off offset:528
	global_load_dwordx4 v[128:131], v[96:97], off offset:16
	global_load_dwordx4 v[108:111], v[96:97], off offset:512
	global_load_dwordx4 v[120:123], v[98:99], off offset:16
	global_load_dwordx4 v[92:95], v[98:99], off offset:512
	global_load_dwordx4 v[124:127], v[98:99], off
	global_load_dwordx4 v[112:115], v[116:117], off offset:528
	global_load_dwordx4 v[140:143], v[116:117], off offset:16
	s_nop 0
	global_load_dwordx4 v[116:119], v[116:117], off offset:512
	v_lshl_add_u32 v196, s24, 8, v221
	v_or_b32_e32 v198, 16, v196
	v_ashrrev_i32_e32 v197, 31, v196
	v_ashrrev_i32_e32 v199, 31, v198
	v_lshlrev_b64 v[96:97], 11, v[196:197]
	v_lshlrev_b64 v[186:187], 11, v[198:199]
	v_lshl_add_u64 v[96:97], s[62:63], 0, v[96:97]
	v_lshlrev_b64 v[184:185], 1, v[194:195]
	v_lshl_add_u64 v[186:187], s[62:63], 0, v[186:187]
	v_lshl_add_u64 v[210:211], v[96:97], 0, v[184:185]
	global_load_dwordx4 v[96:99], v[98:99], off offset:528
	s_nop 0
	global_load_dwordx4 v[202:205], v[210:211], off
	global_load_dwordx4 v[206:209], v[210:211], off offset:256
	v_lshl_add_u64 v[200:201], v[186:187], 0, v[184:185]
	global_load_dwordx4 v[188:191], v[200:201], off
	global_load_dwordx4 v[184:187], v[200:201], off offset:256
	s_waitcnt vmcnt(0)
	v_lshlrev_b32_e32 v232, 16, v202
	v_and_b32_e32 v233, 0xffff0000, v202
	v_lshlrev_b32_e32 v202, 16, v203
	v_and_b32_e32 v203, 0xffff0000, v203
	v_pk_mul_f32 v[202:203], v[146:147], v[202:203]
	v_pk_mul_f32 v[232:233], v[144:145], v[232:233]
	v_lshlrev_b32_e32 v234, 16, v204
	v_and_b32_e32 v235, 0xffff0000, v204
	v_lshlrev_b32_e32 v204, 16, v205
	v_and_b32_e32 v205, 0xffff0000, v205
	v_pk_fma_f32 v[182:183], v[182:183], v[134:135], v[202:203]
	v_pk_fma_f32 v[180:181], v[180:181], v[132:133], v[232:233]
	v_pk_mul_f32 v[204:205], v[142:143], v[204:205]
	v_pk_mul_f32 v[234:235], v[140:141], v[234:235]
	v_mul_f32_e32 v14, v181, v181
	v_mul_f32_e32 v202, v182, v182
	v_fmac_f32_e32 v14, v180, v180
	v_fmac_f32_e32 v202, v183, v183
	v_pk_fma_f32 v[178:179], v[178:179], v[130:131], v[204:205]
	v_pk_fma_f32 v[176:177], v[176:177], v[128:129], v[234:235]
	v_add_f32_e32 v14, v14, v202
	v_mul_f32_e32 v202, v177, v177
	v_mul_f32_e32 v203, v178, v178
	v_fmac_f32_e32 v202, v176, v176
	v_fmac_f32_e32 v203, v179, v179
	v_add_f32_e32 v202, v202, v203
	v_add_f32_e32 v14, v14, v202
	v_pk_mul_f32 v[202:203], v[122:123], v[178:179]
	v_pk_mul_f32 v[178:179], v[120:121], v[176:177]
	v_pk_mul_f32 v[182:183], v[126:127], v[182:183]
	v_pk_mul_f32 v[180:181], v[124:125], v[180:181]
	s_nop 0
	v_cvt_pk_bf16_f32 v176, v180, v181
	v_cvt_pk_bf16_f32 v177, v182, v183
	v_cvt_pk_bf16_f32 v178, v178, v179
	v_cvt_pk_bf16_f32 v179, v202, v203
	global_store_dwordx4 v[210:211], v[176:179], off
	v_lshlrev_b32_e32 v180, 16, v208
	v_and_b32_e32 v181, 0xffff0000, v208
	v_lshlrev_b32_e32 v176, 16, v206
	v_and_b32_e32 v177, 0xffff0000, v206
	v_lshlrev_b32_e32 v178, 16, v207
	v_and_b32_e32 v179, 0xffff0000, v207
	v_pk_mul_f32 v[178:179], v[118:119], v[178:179]
	v_pk_mul_f32 v[176:177], v[116:117], v[176:177]
	v_pk_fma_f32 v[174:175], v[174:175], v[110:111], v[178:179]
	v_pk_fma_f32 v[172:173], v[172:173], v[108:109], v[176:177]
	v_lshlrev_b32_e32 v182, 16, v209
	v_and_b32_e32 v183, 0xffff0000, v209
	v_mul_f32_e32 v176, v173, v173
	v_mul_f32_e32 v177, v174, v174
	v_pk_mul_f32 v[182:183], v[114:115], v[182:183]
	v_pk_mul_f32 v[180:181], v[112:113], v[180:181]
	v_fmac_f32_e32 v176, v172, v172
	v_fmac_f32_e32 v177, v175, v175
	v_add_f32_e32 v176, v176, v177
	v_pk_fma_f32 v[170:171], v[170:171], v[106:107], v[182:183]
	v_pk_fma_f32 v[168:169], v[168:169], v[104:105], v[180:181]
	v_add_f32_e32 v14, v14, v176
	v_mul_f32_e32 v176, v169, v169
	v_mul_f32_e32 v177, v170, v170
	v_fmac_f32_e32 v176, v168, v168
	v_fmac_f32_e32 v177, v171, v171
	v_add_f32_e32 v176, v176, v177
	v_add_f32_e32 v14, v176, v14
	v_mov_b32_e32 v180, v14
	v_pk_mul_f32 v[178:179], v[96:97], v[168:169]
	v_pk_mul_f32 v[172:173], v[92:93], v[172:173]
	v_pk_mul_f32 v[174:175], v[94:95], v[174:175]
	v_pk_mul_f32 v[176:177], v[98:99], v[170:171]
	s_waitcnt lgkmcnt(0)
	v_permlane16_swap_b32_e32 v180, v14
	v_add_f32_e32 v14, v14, v180
	v_mov_b32_e32 v168, v14
	v_cvt_pk_bf16_f32 v170, v172, v173
	v_cvt_pk_bf16_f32 v171, v174, v175
	v_cvt_pk_bf16_f32 v172, v178, v179
	v_cvt_pk_bf16_f32 v173, v176, v177
	global_store_dwordx4 v[210:211], v[170:173], off offset:256
	v_permlane32_swap_b32_e32 v168, v14
	s_and_saveexec_b64 s[10:11], s[0:1]
	s_mov_b64 s[64:65], s[72:73]
	v_readlane_b32 s81, v250, 14
	v_readlane_b32 s82, v250, 13
	s_movk_i32 s60, 0x2c00
	s_cbranch_execz .LBB0_1447
	s_waitcnt lgkmcnt(0)
	v_add_f32_e32 v14, v14, v168
	s_lshl_b32 s38, s26, 2
	v_lshlrev_b64 v[168:169], 6, v[196:197]
	s_ashr_i32 s39, s38, 31
	v_lshl_add_u64 v[168:169], s[64:65], 0, v[168:169]
	v_lshl_add_u64 v[168:169], s[38:39], 2, v[168:169]
	s_lshl_b32 s18, s29, 2
	v_lshl_add_u64 v[168:169], v[168:169], 0, s[18:19]
	global_store_dword v[168:169], v14, off
.LBB0_1447:
	s_or_b64 exec, exec, s[10:11]
	v_or_b32_e32 v176, 32, v196
	v_ashrrev_i32_e32 v177, 31, v176
	s_waitcnt lgkmcnt(0)
	v_lshlrev_b64 v[168:169], 11, v[176:177]
	v_lshl_add_u64 v[168:169], s[62:63], 0, v[168:169]
	v_lshl_add_u64 v[178:179], v[194:195], 1, v[168:169]
	global_load_dwordx4 v[172:175], v[178:179], off
	global_load_dwordx4 v[168:171], v[178:179], off offset:256
	v_lshlrev_b32_e32 v180, 16, v188
	v_and_b32_e32 v181, 0xffff0000, v188
	v_lshlrev_b32_e32 v182, 16, v189
	v_and_b32_e32 v183, 0xffff0000, v189
	v_pk_mul_f32 v[180:181], v[144:145], v[180:181]
	v_pk_mul_f32 v[182:183], v[146:147], v[182:183]
	v_lshlrev_b32_e32 v188, 16, v190
	v_and_b32_e32 v189, 0xffff0000, v190
	v_lshlrev_b32_e32 v190, 16, v191
	v_and_b32_e32 v191, 0xffff0000, v191
	v_pk_fma_f32 v[166:167], v[166:167], v[134:135], v[182:183]
	v_pk_fma_f32 v[164:165], v[164:165], v[132:133], v[180:181]
	v_pk_mul_f32 v[188:189], v[140:141], v[188:189]
	v_pk_mul_f32 v[190:191], v[142:143], v[190:191]
	v_mul_f32_e32 v14, v165, v165
	v_mul_f32_e32 v180, v166, v166
	v_fmac_f32_e32 v14, v164, v164
	v_fmac_f32_e32 v180, v167, v167
	v_pk_fma_f32 v[162:163], v[162:163], v[130:131], v[190:191]
	v_pk_fma_f32 v[160:161], v[160:161], v[128:129], v[188:189]
	v_add_f32_e32 v14, v14, v180
	v_mul_f32_e32 v180, v161, v161
	v_mul_f32_e32 v181, v162, v162
	v_fmac_f32_e32 v180, v160, v160
	v_fmac_f32_e32 v181, v163, v163
	v_add_f32_e32 v180, v180, v181
	v_add_f32_e32 v14, v14, v180
	v_pk_mul_f32 v[180:181], v[122:123], v[162:163]
	v_pk_mul_f32 v[162:163], v[120:121], v[160:161]
	v_pk_mul_f32 v[166:167], v[126:127], v[166:167]
	v_pk_mul_f32 v[164:165], v[124:125], v[164:165]
	s_nop 0
	v_cvt_pk_bf16_f32 v160, v164, v165
	v_cvt_pk_bf16_f32 v161, v166, v167
	v_cvt_pk_bf16_f32 v162, v162, v163
	v_cvt_pk_bf16_f32 v163, v180, v181
	global_store_dwordx4 v[200:201], v[160:163], off
	v_lshlrev_b32_e32 v164, 16, v186
	v_and_b32_e32 v165, 0xffff0000, v186
	v_lshlrev_b32_e32 v160, 16, v184
	v_and_b32_e32 v161, 0xffff0000, v184
	v_lshlrev_b32_e32 v162, 16, v185
	v_and_b32_e32 v163, 0xffff0000, v185
	v_pk_mul_f32 v[160:161], v[116:117], v[160:161]
	v_pk_mul_f32 v[162:163], v[118:119], v[162:163]
	v_pk_fma_f32 v[156:157], v[156:157], v[108:109], v[160:161]
	v_pk_fma_f32 v[158:159], v[158:159], v[110:111], v[162:163]
	v_lshlrev_b32_e32 v166, 16, v187
	v_and_b32_e32 v167, 0xffff0000, v187
	v_mul_f32_e32 v160, v157, v157
	v_mul_f32_e32 v161, v158, v158
	v_pk_mul_f32 v[164:165], v[112:113], v[164:165]
	v_pk_mul_f32 v[166:167], v[114:115], v[166:167]
	v_fmac_f32_e32 v160, v156, v156
	v_fmac_f32_e32 v161, v159, v159
	v_add_f32_e32 v160, v160, v161
	v_pk_fma_f32 v[154:155], v[154:155], v[106:107], v[166:167]
	v_pk_fma_f32 v[152:153], v[152:153], v[104:105], v[164:165]
	v_add_f32_e32 v14, v14, v160
	v_mul_f32_e32 v160, v153, v153
	v_mul_f32_e32 v161, v154, v154
	v_fmac_f32_e32 v160, v152, v152
	v_fmac_f32_e32 v161, v155, v155
	v_add_f32_e32 v160, v160, v161
	v_add_f32_e32 v14, v160, v14
	v_mov_b32_e32 v164, v14
	v_pk_mul_f32 v[162:163], v[96:97], v[152:153]
	v_pk_mul_f32 v[156:157], v[92:93], v[156:157]
	v_pk_mul_f32 v[158:159], v[94:95], v[158:159]
	v_pk_mul_f32 v[160:161], v[98:99], v[154:155]
	s_waitcnt lgkmcnt(0)
	v_permlane16_swap_b32_e32 v164, v14
	v_add_f32_e32 v14, v14, v164
	v_mov_b32_e32 v152, v14
	v_cvt_pk_bf16_f32 v154, v156, v157
	v_cvt_pk_bf16_f32 v155, v158, v159
	v_cvt_pk_bf16_f32 v156, v162, v163
	v_cvt_pk_bf16_f32 v157, v160, v161
	global_store_dwordx4 v[200:201], v[154:157], off offset:256
	v_permlane32_swap_b32_e32 v152, v14
	s_and_saveexec_b64 s[10:11], s[0:1]
	s_movk_i32 s72, 0x80
	s_mov_b32 s66, 0x8000
	s_mov_b32 s67, 0x10000
	s_mov_b32 s68, 0x18000
	s_mov_b32 s69, 0xffff0000
	s_movk_i32 s73, 0x1600
	s_cbranch_execz .LBB0_1449
	s_waitcnt lgkmcnt(0)
	v_add_f32_e32 v14, v14, v152
	s_lshl_b32 s38, s26, 2
	v_lshlrev_b64 v[152:153], 6, v[198:199]
	s_ashr_i32 s39, s38, 31
	v_lshl_add_u64 v[152:153], s[64:65], 0, v[152:153]
	v_lshl_add_u64 v[152:153], s[38:39], 2, v[152:153]
	s_lshl_b32 s18, s29, 2
	v_lshl_add_u64 v[152:153], v[152:153], 0, s[18:19]
	global_store_dword v[152:153], v14, off
.LBB0_1449:
	s_or_b64 exec, exec, s[10:11]
	v_or_b32_e32 v160, 48, v196
	v_ashrrev_i32_e32 v161, 31, v160
	s_waitcnt lgkmcnt(0)
	v_lshlrev_b64 v[152:153], 11, v[160:161]
	v_lshl_add_u64 v[152:153], s[62:63], 0, v[152:153]
	v_lshl_add_u64 v[162:163], v[194:195], 1, v[152:153]
	global_load_dwordx4 v[156:159], v[162:163], off
	global_load_dwordx4 v[152:155], v[162:163], off offset:256
	s_waitcnt vmcnt(5)
	v_lshlrev_b32_e32 v164, 16, v172
	v_and_b32_e32 v165, 0xffff0000, v172
	v_lshlrev_b32_e32 v166, 16, v173
	v_and_b32_e32 v167, 0xffff0000, v173
	v_pk_mul_f32 v[164:165], v[144:145], v[164:165]
	v_pk_mul_f32 v[166:167], v[146:147], v[166:167]
	v_lshlrev_b32_e32 v172, 16, v174
	v_and_b32_e32 v173, 0xffff0000, v174
	v_lshlrev_b32_e32 v174, 16, v175
	v_and_b32_e32 v175, 0xffff0000, v175
	v_pk_fma_f32 v[150:151], v[150:151], v[134:135], v[166:167]
	v_pk_fma_f32 v[148:149], v[148:149], v[132:133], v[164:165]
	v_pk_mul_f32 v[172:173], v[140:141], v[172:173]
	v_pk_mul_f32 v[174:175], v[142:143], v[174:175]
	v_mul_f32_e32 v14, v149, v149
	v_mul_f32_e32 v164, v150, v150
	v_fmac_f32_e32 v14, v148, v148
	v_fmac_f32_e32 v164, v151, v151
	v_pk_fma_f32 v[138:139], v[138:139], v[130:131], v[174:175]
	v_pk_fma_f32 v[136:137], v[136:137], v[128:129], v[172:173]
	v_add_f32_e32 v14, v14, v164
	v_mul_f32_e32 v164, v137, v137
	v_mul_f32_e32 v165, v138, v138
	v_fmac_f32_e32 v164, v136, v136
	v_fmac_f32_e32 v165, v139, v139
	v_add_f32_e32 v164, v164, v165
	v_add_f32_e32 v14, v14, v164
	v_pk_mul_f32 v[164:165], v[122:123], v[138:139]
	v_pk_mul_f32 v[138:139], v[120:121], v[136:137]
	v_pk_mul_f32 v[150:151], v[126:127], v[150:151]
	v_pk_mul_f32 v[148:149], v[124:125], v[148:149]
	s_nop 0
	v_cvt_pk_bf16_f32 v136, v148, v149
	v_cvt_pk_bf16_f32 v137, v150, v151
	v_cvt_pk_bf16_f32 v138, v138, v139
	v_cvt_pk_bf16_f32 v139, v164, v165
	global_store_dwordx4 v[178:179], v[136:139], off
	s_waitcnt vmcnt(5)
	v_lshlrev_b32_e32 v148, 16, v170
	v_and_b32_e32 v149, 0xffff0000, v170
	v_lshlrev_b32_e32 v136, 16, v168
	v_and_b32_e32 v137, 0xffff0000, v168
	v_lshlrev_b32_e32 v138, 16, v169
	v_and_b32_e32 v139, 0xffff0000, v169
	v_pk_mul_f32 v[136:137], v[116:117], v[136:137]
	v_pk_mul_f32 v[138:139], v[118:119], v[138:139]
	v_pk_fma_f32 v[100:101], v[100:101], v[108:109], v[136:137]
	v_pk_fma_f32 v[102:103], v[102:103], v[110:111], v[138:139]
	v_lshlrev_b32_e32 v150, 16, v171
	v_and_b32_e32 v151, 0xffff0000, v171
	v_mul_f32_e32 v136, v101, v101
	v_mul_f32_e32 v137, v102, v102
	v_pk_mul_f32 v[148:149], v[112:113], v[148:149]
	v_pk_mul_f32 v[150:151], v[114:115], v[150:151]
	v_fmac_f32_e32 v136, v100, v100
	v_fmac_f32_e32 v137, v103, v103
	v_add_f32_e32 v136, v136, v137
	v_pk_fma_f32 v[90:91], v[90:91], v[106:107], v[150:151]
	v_pk_fma_f32 v[88:89], v[88:89], v[104:105], v[148:149]
	v_add_f32_e32 v14, v14, v136
	v_mul_f32_e32 v136, v89, v89
	v_mul_f32_e32 v137, v90, v90
	v_fmac_f32_e32 v136, v88, v88
	v_fmac_f32_e32 v137, v91, v91
	v_add_f32_e32 v136, v136, v137
	v_add_f32_e32 v14, v136, v14
	v_mov_b32_e32 v138, v14
	v_pk_mul_f32 v[136:137], v[96:97], v[88:89]
	v_pk_mul_f32 v[102:103], v[94:95], v[102:103]
	v_pk_mul_f32 v[100:101], v[92:93], v[100:101]
	v_pk_mul_f32 v[90:91], v[98:99], v[90:91]
	s_waitcnt lgkmcnt(0)
	v_permlane16_swap_b32_e32 v138, v14
	v_add_f32_e32 v14, v14, v138
	v_mov_b32_e32 v88, v14
	v_cvt_pk_bf16_f32 v100, v100, v101
	v_cvt_pk_bf16_f32 v101, v102, v103
	v_cvt_pk_bf16_f32 v102, v136, v137
	v_cvt_pk_bf16_f32 v103, v90, v91
	global_store_dwordx4 v[178:179], v[100:103], off offset:256
	v_permlane32_swap_b32_e32 v88, v14
	s_and_saveexec_b64 s[10:11], s[0:1]
	s_cbranch_execz .LBB0_1451
	s_waitcnt lgkmcnt(0)
	v_add_f32_e32 v14, v14, v88
	s_lshl_b32 s38, s26, 2
	v_lshlrev_b64 v[88:89], 6, v[176:177]
	s_ashr_i32 s39, s38, 31
	v_lshl_add_u64 v[88:89], s[64:65], 0, v[88:89]
	v_lshl_add_u64 v[88:89], s[38:39], 2, v[88:89]
	s_lshl_b32 s18, s29, 2
	v_lshl_add_u64 v[88:89], v[88:89], 0, s[18:19]
	global_store_dword v[88:89], v14, off
.LBB0_1451:
	s_or_b64 exec, exec, s[10:11]
	v_add_u32_e32 v136, 0x80, v196
	v_ashrrev_i32_e32 v137, 31, v136
	s_waitcnt lgkmcnt(0)
	v_lshlrev_b64 v[88:89], 11, v[136:137]
	v_lshl_add_u64 v[88:89], s[62:63], 0, v[88:89]
	v_lshl_add_u64 v[138:139], v[194:195], 1, v[88:89]
	global_load_dwordx4 v[100:103], v[138:139], off
	global_load_dwordx4 v[88:91], v[138:139], off offset:256
	s_waitcnt vmcnt(5)
	v_lshlrev_b32_e32 v148, 16, v156
	v_and_b32_e32 v149, 0xffff0000, v156
	v_lshlrev_b32_e32 v150, 16, v157
	v_and_b32_e32 v151, 0xffff0000, v157
	v_pk_mul_f32 v[148:149], v[144:145], v[148:149]
	v_pk_mul_f32 v[150:151], v[146:147], v[150:151]
	v_lshlrev_b32_e32 v156, 16, v158
	v_and_b32_e32 v157, 0xffff0000, v158
	v_lshlrev_b32_e32 v158, 16, v159
	v_and_b32_e32 v159, 0xffff0000, v159
	v_pk_fma_f32 v[86:87], v[86:87], v[134:135], v[150:151]
	v_pk_fma_f32 v[84:85], v[84:85], v[132:133], v[148:149]
	v_pk_mul_f32 v[156:157], v[140:141], v[156:157]
	v_pk_mul_f32 v[158:159], v[142:143], v[158:159]
	v_mul_f32_e32 v14, v85, v85
	v_mul_f32_e32 v148, v86, v86
	v_fmac_f32_e32 v14, v84, v84
	v_fmac_f32_e32 v148, v87, v87
	v_pk_fma_f32 v[82:83], v[82:83], v[130:131], v[158:159]
	v_pk_fma_f32 v[80:81], v[80:81], v[128:129], v[156:157]
	v_add_f32_e32 v14, v14, v148
	v_mul_f32_e32 v148, v81, v81
	v_mul_f32_e32 v149, v82, v82
	v_fmac_f32_e32 v148, v80, v80
	v_fmac_f32_e32 v149, v83, v83
	v_add_f32_e32 v148, v148, v149
	v_add_f32_e32 v14, v14, v148
	v_pk_mul_f32 v[148:149], v[122:123], v[82:83]
	v_pk_mul_f32 v[82:83], v[120:121], v[80:81]
	v_pk_mul_f32 v[86:87], v[126:127], v[86:87]
	v_pk_mul_f32 v[84:85], v[124:125], v[84:85]
	s_nop 0
	v_cvt_pk_bf16_f32 v80, v84, v85
	v_cvt_pk_bf16_f32 v81, v86, v87
	v_cvt_pk_bf16_f32 v82, v82, v83
	v_cvt_pk_bf16_f32 v83, v148, v149
	global_store_dwordx4 v[162:163], v[80:83], off
	s_waitcnt vmcnt(5)
	v_lshlrev_b32_e32 v84, 16, v154
	v_and_b32_e32 v85, 0xffff0000, v154
	v_lshlrev_b32_e32 v80, 16, v152
	v_and_b32_e32 v81, 0xffff0000, v152
	v_lshlrev_b32_e32 v82, 16, v153
	v_and_b32_e32 v83, 0xffff0000, v153
	v_pk_mul_f32 v[80:81], v[116:117], v[80:81]
	v_pk_mul_f32 v[82:83], v[118:119], v[82:83]
	v_pk_fma_f32 v[76:77], v[76:77], v[108:109], v[80:81]
	v_pk_fma_f32 v[78:79], v[78:79], v[110:111], v[82:83]
	v_lshlrev_b32_e32 v86, 16, v155
	v_and_b32_e32 v87, 0xffff0000, v155
	v_mul_f32_e32 v80, v77, v77
	v_mul_f32_e32 v81, v78, v78
	v_pk_mul_f32 v[84:85], v[112:113], v[84:85]
	v_pk_mul_f32 v[86:87], v[114:115], v[86:87]
	v_fmac_f32_e32 v80, v76, v76
	v_fmac_f32_e32 v81, v79, v79
	v_add_f32_e32 v80, v80, v81
	v_pk_fma_f32 v[74:75], v[74:75], v[106:107], v[86:87]
	v_pk_fma_f32 v[72:73], v[72:73], v[104:105], v[84:85]
	v_add_f32_e32 v14, v14, v80
	v_mul_f32_e32 v80, v73, v73
	v_mul_f32_e32 v81, v74, v74
	v_fmac_f32_e32 v80, v72, v72
	v_fmac_f32_e32 v81, v75, v75
	v_add_f32_e32 v80, v80, v81
	v_add_f32_e32 v14, v80, v14
	v_mov_b32_e32 v84, v14
	v_pk_mul_f32 v[82:83], v[96:97], v[72:73]
	v_pk_mul_f32 v[76:77], v[92:93], v[76:77]
	v_pk_mul_f32 v[78:79], v[94:95], v[78:79]
	v_pk_mul_f32 v[80:81], v[98:99], v[74:75]
	s_waitcnt lgkmcnt(0)
	v_permlane16_swap_b32_e32 v84, v14
	v_add_f32_e32 v14, v14, v84
	v_mov_b32_e32 v72, v14
	v_cvt_pk_bf16_f32 v74, v76, v77
	v_cvt_pk_bf16_f32 v75, v78, v79
	v_cvt_pk_bf16_f32 v76, v82, v83
	v_cvt_pk_bf16_f32 v77, v80, v81
	global_store_dwordx4 v[162:163], v[74:77], off offset:256
	v_permlane32_swap_b32_e32 v72, v14
	s_and_saveexec_b64 s[10:11], s[0:1]
	s_cbranch_execz .LBB0_1453
	s_waitcnt lgkmcnt(0)
	v_add_f32_e32 v14, v14, v72
	s_lshl_b32 s38, s26, 2
	v_lshlrev_b64 v[72:73], 6, v[160:161]
	s_ashr_i32 s39, s38, 31
	v_lshl_add_u64 v[72:73], s[64:65], 0, v[72:73]
	v_lshl_add_u64 v[72:73], s[38:39], 2, v[72:73]
	s_lshl_b32 s18, s29, 2
	v_lshl_add_u64 v[72:73], v[72:73], 0, s[18:19]
	global_store_dword v[72:73], v14, off
.LBB0_1453:
	s_or_b64 exec, exec, s[10:11]
	v_or_b32_e32 v80, 16, v136
	v_ashrrev_i32_e32 v81, 31, v80
	s_waitcnt lgkmcnt(0)
	v_lshlrev_b64 v[72:73], 11, v[80:81]
	v_lshl_add_u64 v[72:73], s[62:63], 0, v[72:73]
	v_lshl_add_u64 v[82:83], v[194:195], 1, v[72:73]
	global_load_dwordx4 v[76:79], v[82:83], off
	global_load_dwordx4 v[72:75], v[82:83], off offset:256
	s_waitcnt vmcnt(5)
	v_lshlrev_b32_e32 v84, 16, v100
	v_and_b32_e32 v85, 0xffff0000, v100
	v_lshlrev_b32_e32 v86, 16, v101
	v_and_b32_e32 v87, 0xffff0000, v101
	v_pk_mul_f32 v[84:85], v[144:145], v[84:85]
	v_pk_mul_f32 v[86:87], v[146:147], v[86:87]
	v_lshlrev_b32_e32 v100, 16, v102
	v_and_b32_e32 v101, 0xffff0000, v102
	v_lshlrev_b32_e32 v102, 16, v103
	v_and_b32_e32 v103, 0xffff0000, v103
	v_pk_fma_f32 v[70:71], v[70:71], v[134:135], v[86:87]
	v_pk_fma_f32 v[68:69], v[68:69], v[132:133], v[84:85]
	v_pk_mul_f32 v[100:101], v[140:141], v[100:101]
	v_pk_mul_f32 v[102:103], v[142:143], v[102:103]
	v_mul_f32_e32 v14, v69, v69
	v_mul_f32_e32 v84, v70, v70
	v_fmac_f32_e32 v14, v68, v68
	v_fmac_f32_e32 v84, v71, v71
	v_pk_fma_f32 v[66:67], v[66:67], v[130:131], v[102:103]
	v_pk_fma_f32 v[64:65], v[64:65], v[128:129], v[100:101]
	v_add_f32_e32 v14, v14, v84
	v_mul_f32_e32 v84, v65, v65
	v_mul_f32_e32 v85, v66, v66
	v_fmac_f32_e32 v84, v64, v64
	v_fmac_f32_e32 v85, v67, v67
	v_add_f32_e32 v84, v84, v85
	v_add_f32_e32 v14, v14, v84
	v_pk_mul_f32 v[84:85], v[122:123], v[66:67]
	v_pk_mul_f32 v[66:67], v[120:121], v[64:65]
	v_pk_mul_f32 v[70:71], v[126:127], v[70:71]
	v_pk_mul_f32 v[68:69], v[124:125], v[68:69]
	s_nop 0
	v_cvt_pk_bf16_f32 v64, v68, v69
	v_cvt_pk_bf16_f32 v65, v70, v71
	v_cvt_pk_bf16_f32 v66, v66, v67
	v_cvt_pk_bf16_f32 v67, v84, v85
	global_store_dwordx4 v[138:139], v[64:67], off
	s_waitcnt vmcnt(5)
	v_lshlrev_b32_e32 v68, 16, v90
	v_and_b32_e32 v69, 0xffff0000, v90
	v_lshlrev_b32_e32 v64, 16, v88
	v_and_b32_e32 v65, 0xffff0000, v88
	v_lshlrev_b32_e32 v66, 16, v89
	v_and_b32_e32 v67, 0xffff0000, v89
	v_pk_mul_f32 v[64:65], v[116:117], v[64:65]
	v_pk_mul_f32 v[66:67], v[118:119], v[66:67]
	v_pk_fma_f32 v[60:61], v[60:61], v[108:109], v[64:65]
	v_pk_fma_f32 v[62:63], v[62:63], v[110:111], v[66:67]
	v_lshlrev_b32_e32 v70, 16, v91
	v_and_b32_e32 v71, 0xffff0000, v91
	v_mul_f32_e32 v64, v61, v61
	v_mul_f32_e32 v65, v62, v62
	v_pk_mul_f32 v[68:69], v[112:113], v[68:69]
	v_pk_mul_f32 v[70:71], v[114:115], v[70:71]
	v_fmac_f32_e32 v64, v60, v60
	v_fmac_f32_e32 v65, v63, v63
	v_add_f32_e32 v64, v64, v65
	v_pk_fma_f32 v[58:59], v[58:59], v[106:107], v[70:71]
	v_pk_fma_f32 v[56:57], v[56:57], v[104:105], v[68:69]
	v_add_f32_e32 v14, v14, v64
	v_mul_f32_e32 v64, v57, v57
	v_mul_f32_e32 v65, v58, v58
	v_fmac_f32_e32 v64, v56, v56
	v_fmac_f32_e32 v65, v59, v59
	v_add_f32_e32 v64, v64, v65
	v_add_f32_e32 v14, v64, v14
	v_mov_b32_e32 v68, v14
	v_pk_mul_f32 v[66:67], v[96:97], v[56:57]
	v_pk_mul_f32 v[60:61], v[92:93], v[60:61]
	v_pk_mul_f32 v[62:63], v[94:95], v[62:63]
	v_pk_mul_f32 v[64:65], v[98:99], v[58:59]
	s_waitcnt lgkmcnt(0)
	v_permlane16_swap_b32_e32 v68, v14
	v_add_f32_e32 v14, v14, v68
	v_mov_b32_e32 v56, v14
	v_cvt_pk_bf16_f32 v58, v60, v61
	v_cvt_pk_bf16_f32 v59, v62, v63
	v_cvt_pk_bf16_f32 v60, v66, v67
	v_cvt_pk_bf16_f32 v61, v64, v65
	global_store_dwordx4 v[138:139], v[58:61], off offset:256
	v_permlane32_swap_b32_e32 v56, v14
	s_and_saveexec_b64 s[10:11], s[0:1]
	s_cbranch_execz .LBB0_1455
	s_waitcnt lgkmcnt(0)
	v_add_f32_e32 v14, v14, v56
	s_lshl_b32 s38, s26, 2
	v_lshlrev_b64 v[56:57], 6, v[136:137]
	s_ashr_i32 s39, s38, 31
	v_lshl_add_u64 v[56:57], s[64:65], 0, v[56:57]
	v_lshl_add_u64 v[56:57], s[38:39], 2, v[56:57]
	s_lshl_b32 s18, s29, 2
	v_lshl_add_u64 v[56:57], v[56:57], 0, s[18:19]
	global_store_dword v[56:57], v14, off
.LBB0_1455:
	s_or_b64 exec, exec, s[10:11]
	v_or_b32_e32 v64, 32, v136
	v_ashrrev_i32_e32 v65, 31, v64
	s_waitcnt lgkmcnt(0)
	v_lshlrev_b64 v[56:57], 11, v[64:65]
	v_lshl_add_u64 v[56:57], s[62:63], 0, v[56:57]
	v_lshl_add_u64 v[66:67], v[194:195], 1, v[56:57]
	global_load_dwordx4 v[60:63], v[66:67], off
	global_load_dwordx4 v[56:59], v[66:67], off offset:256
	s_waitcnt vmcnt(5)
	v_lshlrev_b32_e32 v68, 16, v76
	v_and_b32_e32 v69, 0xffff0000, v76
	v_lshlrev_b32_e32 v70, 16, v77
	v_and_b32_e32 v71, 0xffff0000, v77
	v_pk_mul_f32 v[68:69], v[144:145], v[68:69]
	v_pk_mul_f32 v[70:71], v[146:147], v[70:71]
	v_lshlrev_b32_e32 v76, 16, v78
	v_and_b32_e32 v77, 0xffff0000, v78
	v_lshlrev_b32_e32 v78, 16, v79
	v_and_b32_e32 v79, 0xffff0000, v79
	v_pk_fma_f32 v[54:55], v[54:55], v[134:135], v[70:71]
	v_pk_fma_f32 v[52:53], v[52:53], v[132:133], v[68:69]
	v_pk_mul_f32 v[76:77], v[140:141], v[76:77]
	v_pk_mul_f32 v[78:79], v[142:143], v[78:79]
	v_mul_f32_e32 v14, v53, v53
	v_mul_f32_e32 v68, v54, v54
	v_fmac_f32_e32 v14, v52, v52
	v_fmac_f32_e32 v68, v55, v55
	v_pk_fma_f32 v[50:51], v[50:51], v[130:131], v[78:79]
	v_pk_fma_f32 v[48:49], v[48:49], v[128:129], v[76:77]
	v_add_f32_e32 v14, v14, v68
	v_mul_f32_e32 v68, v49, v49
	v_mul_f32_e32 v69, v50, v50
	v_fmac_f32_e32 v68, v48, v48
	v_fmac_f32_e32 v69, v51, v51
	v_add_f32_e32 v68, v68, v69
	v_add_f32_e32 v14, v14, v68
	v_pk_mul_f32 v[68:69], v[122:123], v[50:51]
	v_pk_mul_f32 v[50:51], v[120:121], v[48:49]
	v_pk_mul_f32 v[54:55], v[126:127], v[54:55]
	v_pk_mul_f32 v[52:53], v[124:125], v[52:53]
	s_nop 0
	v_cvt_pk_bf16_f32 v48, v52, v53
	v_cvt_pk_bf16_f32 v49, v54, v55
	v_cvt_pk_bf16_f32 v50, v50, v51
	v_cvt_pk_bf16_f32 v51, v68, v69
	global_store_dwordx4 v[82:83], v[48:51], off
	s_waitcnt vmcnt(5)
	v_lshlrev_b32_e32 v52, 16, v74
	v_and_b32_e32 v53, 0xffff0000, v74
	v_lshlrev_b32_e32 v48, 16, v72
	v_and_b32_e32 v49, 0xffff0000, v72
	v_lshlrev_b32_e32 v50, 16, v73
	v_and_b32_e32 v51, 0xffff0000, v73
	v_pk_mul_f32 v[48:49], v[116:117], v[48:49]
	v_pk_mul_f32 v[50:51], v[118:119], v[50:51]
	v_pk_fma_f32 v[44:45], v[44:45], v[108:109], v[48:49]
	v_pk_fma_f32 v[46:47], v[46:47], v[110:111], v[50:51]
	v_lshlrev_b32_e32 v54, 16, v75
	v_and_b32_e32 v55, 0xffff0000, v75
	v_mul_f32_e32 v48, v45, v45
	v_mul_f32_e32 v49, v46, v46
	v_pk_mul_f32 v[52:53], v[112:113], v[52:53]
	v_pk_mul_f32 v[54:55], v[114:115], v[54:55]
	v_fmac_f32_e32 v48, v44, v44
	v_fmac_f32_e32 v49, v47, v47
	v_add_f32_e32 v48, v48, v49
	v_pk_fma_f32 v[42:43], v[42:43], v[106:107], v[54:55]
	v_pk_fma_f32 v[40:41], v[40:41], v[104:105], v[52:53]
	v_add_f32_e32 v14, v14, v48
	v_mul_f32_e32 v48, v41, v41
	v_mul_f32_e32 v49, v42, v42
	v_fmac_f32_e32 v48, v40, v40
	v_fmac_f32_e32 v49, v43, v43
	v_add_f32_e32 v48, v48, v49
	v_add_f32_e32 v14, v48, v14
	v_mov_b32_e32 v52, v14
	v_pk_mul_f32 v[50:51], v[96:97], v[40:41]
	v_pk_mul_f32 v[44:45], v[92:93], v[44:45]
	v_pk_mul_f32 v[46:47], v[94:95], v[46:47]
	v_pk_mul_f32 v[48:49], v[98:99], v[42:43]
	s_waitcnt lgkmcnt(0)
	v_permlane16_swap_b32_e32 v52, v14
	v_add_f32_e32 v14, v14, v52
	v_mov_b32_e32 v40, v14
	v_cvt_pk_bf16_f32 v42, v44, v45
	v_cvt_pk_bf16_f32 v43, v46, v47
	v_cvt_pk_bf16_f32 v44, v50, v51
	v_cvt_pk_bf16_f32 v45, v48, v49
	global_store_dwordx4 v[82:83], v[42:45], off offset:256
	v_permlane32_swap_b32_e32 v40, v14
	s_and_saveexec_b64 s[10:11], s[0:1]
	s_cbranch_execz .LBB0_1457
	s_waitcnt lgkmcnt(0)
	v_add_f32_e32 v14, v14, v40
	s_lshl_b32 s38, s26, 2
	v_lshlrev_b64 v[40:41], 6, v[80:81]
	s_ashr_i32 s39, s38, 31
	v_lshl_add_u64 v[40:41], s[64:65], 0, v[40:41]
	v_lshl_add_u64 v[40:41], s[38:39], 2, v[40:41]
	s_lshl_b32 s18, s29, 2
	v_lshl_add_u64 v[40:41], v[40:41], 0, s[18:19]
	global_store_dword v[40:41], v14, off
.LBB0_1457:
	s_or_b64 exec, exec, s[10:11]
	v_or_b32_e32 v48, 48, v136
	v_ashrrev_i32_e32 v49, 31, v48
	s_waitcnt lgkmcnt(0)
	v_lshlrev_b64 v[40:41], 11, v[48:49]
	v_lshl_add_u64 v[40:41], s[62:63], 0, v[40:41]
	v_lshl_add_u64 v[50:51], v[194:195], 1, v[40:41]
	global_load_dwordx4 v[44:47], v[50:51], off
	global_load_dwordx4 v[40:43], v[50:51], off offset:256
	s_waitcnt vmcnt(5)
	v_lshlrev_b32_e32 v52, 16, v60
	v_and_b32_e32 v53, 0xffff0000, v60
	v_lshlrev_b32_e32 v54, 16, v61
	v_and_b32_e32 v55, 0xffff0000, v61
	v_pk_mul_f32 v[52:53], v[144:145], v[52:53]
	v_pk_mul_f32 v[54:55], v[146:147], v[54:55]
	v_lshlrev_b32_e32 v60, 16, v62
	v_and_b32_e32 v61, 0xffff0000, v62
	v_lshlrev_b32_e32 v62, 16, v63
	v_and_b32_e32 v63, 0xffff0000, v63
	v_pk_fma_f32 v[38:39], v[38:39], v[134:135], v[54:55]
	v_pk_fma_f32 v[36:37], v[36:37], v[132:133], v[52:53]
	v_pk_mul_f32 v[60:61], v[140:141], v[60:61]
	v_pk_mul_f32 v[62:63], v[142:143], v[62:63]
	v_mul_f32_e32 v14, v37, v37
	v_mul_f32_e32 v52, v38, v38
	v_fmac_f32_e32 v14, v36, v36
	v_fmac_f32_e32 v52, v39, v39
	v_pk_fma_f32 v[34:35], v[34:35], v[130:131], v[62:63]
	v_pk_fma_f32 v[32:33], v[32:33], v[128:129], v[60:61]
	v_add_f32_e32 v14, v14, v52
	v_mul_f32_e32 v52, v33, v33
	v_mul_f32_e32 v53, v34, v34
	v_fmac_f32_e32 v52, v32, v32
	v_fmac_f32_e32 v53, v35, v35
	v_add_f32_e32 v52, v52, v53
	v_add_f32_e32 v14, v14, v52
	v_pk_mul_f32 v[52:53], v[122:123], v[34:35]
	v_pk_mul_f32 v[34:35], v[120:121], v[32:33]
	v_pk_mul_f32 v[38:39], v[126:127], v[38:39]
	v_pk_mul_f32 v[36:37], v[124:125], v[36:37]
	s_nop 0
	v_cvt_pk_bf16_f32 v32, v36, v37
	v_cvt_pk_bf16_f32 v33, v38, v39
	v_cvt_pk_bf16_f32 v34, v34, v35
	v_cvt_pk_bf16_f32 v35, v52, v53
	global_store_dwordx4 v[66:67], v[32:35], off
	s_waitcnt vmcnt(5)
	v_lshlrev_b32_e32 v36, 16, v58
	v_and_b32_e32 v37, 0xffff0000, v58
	v_lshlrev_b32_e32 v32, 16, v56
	v_and_b32_e32 v33, 0xffff0000, v56
	v_lshlrev_b32_e32 v34, 16, v57
	v_and_b32_e32 v35, 0xffff0000, v57
	v_pk_mul_f32 v[32:33], v[116:117], v[32:33]
	v_pk_mul_f32 v[34:35], v[118:119], v[34:35]
	v_pk_fma_f32 v[28:29], v[28:29], v[108:109], v[32:33]
	v_pk_fma_f32 v[30:31], v[30:31], v[110:111], v[34:35]
	v_lshlrev_b32_e32 v38, 16, v59
	v_and_b32_e32 v39, 0xffff0000, v59
	v_mul_f32_e32 v32, v29, v29
	v_mul_f32_e32 v33, v30, v30
	v_pk_mul_f32 v[36:37], v[112:113], v[36:37]
	v_pk_mul_f32 v[38:39], v[114:115], v[38:39]
	v_fmac_f32_e32 v32, v28, v28
	v_fmac_f32_e32 v33, v31, v31
	v_add_f32_e32 v32, v32, v33
	v_pk_fma_f32 v[26:27], v[26:27], v[106:107], v[38:39]
	v_pk_fma_f32 v[24:25], v[24:25], v[104:105], v[36:37]
	v_add_f32_e32 v14, v14, v32
	v_mul_f32_e32 v32, v25, v25
	v_mul_f32_e32 v33, v26, v26
	v_fmac_f32_e32 v32, v24, v24
	v_fmac_f32_e32 v33, v27, v27
	v_add_f32_e32 v32, v32, v33
	v_add_f32_e32 v14, v32, v14
	v_mov_b32_e32 v36, v14
	v_pk_mul_f32 v[34:35], v[96:97], v[24:25]
	v_pk_mul_f32 v[28:29], v[92:93], v[28:29]
	v_pk_mul_f32 v[30:31], v[94:95], v[30:31]
	v_pk_mul_f32 v[32:33], v[98:99], v[26:27]
	s_waitcnt lgkmcnt(0)
	v_permlane16_swap_b32_e32 v36, v14
	v_add_f32_e32 v14, v14, v36
	v_mov_b32_e32 v24, v14
	v_cvt_pk_bf16_f32 v26, v28, v29
	v_cvt_pk_bf16_f32 v27, v30, v31
	v_cvt_pk_bf16_f32 v28, v34, v35
	v_cvt_pk_bf16_f32 v29, v32, v33
	global_store_dwordx4 v[66:67], v[26:29], off offset:256
	v_permlane32_swap_b32_e32 v24, v14
	s_and_saveexec_b64 s[10:11], s[0:1]
	s_cbranch_execz .LBB0_1459
	s_waitcnt lgkmcnt(0)
	v_add_f32_e32 v14, v14, v24
	s_lshl_b32 s38, s26, 2
	v_lshlrev_b64 v[24:25], 6, v[64:65]
	s_ashr_i32 s39, s38, 31
	v_lshl_add_u64 v[24:25], s[64:65], 0, v[24:25]
	v_lshl_add_u64 v[24:25], s[38:39], 2, v[24:25]
	s_lshl_b32 s18, s29, 2
	v_lshl_add_u64 v[24:25], v[24:25], 0, s[18:19]
	global_store_dword v[24:25], v14, off
.LBB0_1459:
	s_or_b64 exec, exec, s[10:11]
	s_waitcnt vmcnt(3) lgkmcnt(0)
	v_lshlrev_b32_e32 v24, 16, v44
	v_and_b32_e32 v25, 0xffff0000, v44
	v_lshlrev_b32_e32 v26, 16, v45
	v_and_b32_e32 v27, 0xffff0000, v45
	v_pk_mul_f32 v[24:25], v[144:145], v[24:25]
	v_pk_mul_f32 v[26:27], v[146:147], v[26:27]
	v_lshlrev_b32_e32 v28, 16, v46
	v_and_b32_e32 v29, 0xffff0000, v46
	v_lshlrev_b32_e32 v30, 16, v47
	v_and_b32_e32 v31, 0xffff0000, v47
	v_pk_fma_f32 v[22:23], v[22:23], v[134:135], v[26:27]
	v_pk_fma_f32 v[20:21], v[20:21], v[132:133], v[24:25]
	v_pk_mul_f32 v[28:29], v[140:141], v[28:29]
	v_pk_mul_f32 v[30:31], v[142:143], v[30:31]
	v_mul_f32_e32 v14, v21, v21
	v_mul_f32_e32 v24, v22, v22
	v_fmac_f32_e32 v14, v20, v20
	v_fmac_f32_e32 v24, v23, v23
	v_pk_fma_f32 v[18:19], v[18:19], v[130:131], v[30:31]
	v_pk_fma_f32 v[16:17], v[16:17], v[128:129], v[28:29]
	v_add_f32_e32 v14, v14, v24
	v_mul_f32_e32 v24, v17, v17
	v_mul_f32_e32 v25, v18, v18
	v_fmac_f32_e32 v24, v16, v16
	v_fmac_f32_e32 v25, v19, v19
	v_add_f32_e32 v24, v24, v25
	v_add_f32_e32 v14, v14, v24
	v_pk_mul_f32 v[24:25], v[122:123], v[18:19]
	v_pk_mul_f32 v[18:19], v[120:121], v[16:17]
	v_pk_mul_f32 v[22:23], v[126:127], v[22:23]
	v_pk_mul_f32 v[20:21], v[124:125], v[20:21]
	s_nop 0
	v_cvt_pk_bf16_f32 v16, v20, v21
	v_cvt_pk_bf16_f32 v17, v22, v23
	v_cvt_pk_bf16_f32 v18, v18, v19
	v_cvt_pk_bf16_f32 v19, v24, v25
	global_store_dwordx4 v[50:51], v[16:19], off
	s_waitcnt vmcnt(3)
	v_lshlrev_b32_e32 v20, 16, v42
	v_and_b32_e32 v21, 0xffff0000, v42
	v_lshlrev_b32_e32 v16, 16, v40
	v_and_b32_e32 v17, 0xffff0000, v40
	v_lshlrev_b32_e32 v18, 16, v41
	v_and_b32_e32 v19, 0xffff0000, v41
	v_pk_mul_f32 v[16:17], v[116:117], v[16:17]
	v_pk_mul_f32 v[18:19], v[118:119], v[18:19]
	v_pk_fma_f32 v[10:11], v[10:11], v[108:109], v[16:17]
	v_pk_fma_f32 v[12:13], v[12:13], v[110:111], v[18:19]
	v_lshlrev_b32_e32 v22, 16, v43
	v_and_b32_e32 v23, 0xffff0000, v43
	v_mul_f32_e32 v16, v11, v11
	v_mul_f32_e32 v17, v12, v12
	v_pk_mul_f32 v[20:21], v[112:113], v[20:21]
	v_pk_mul_f32 v[22:23], v[114:115], v[22:23]
	v_fmac_f32_e32 v16, v10, v10
	v_fmac_f32_e32 v17, v13, v13
	v_add_f32_e32 v16, v16, v17
	v_pk_fma_f32 v[8:9], v[8:9], v[106:107], v[22:23]
	v_pk_fma_f32 v[6:7], v[6:7], v[104:105], v[20:21]
	v_add_f32_e32 v14, v14, v16
	v_mul_f32_e32 v16, v7, v7
	v_mul_f32_e32 v17, v8, v8
	v_fmac_f32_e32 v16, v6, v6
	v_fmac_f32_e32 v17, v9, v9
	v_add_f32_e32 v16, v16, v17
	v_add_f32_e32 v14, v16, v14
	v_mov_b32_e32 v20, v14
	v_pk_mul_f32 v[18:19], v[96:97], v[6:7]
	v_pk_mul_f32 v[10:11], v[92:93], v[10:11]
	v_pk_mul_f32 v[12:13], v[94:95], v[12:13]
	v_pk_mul_f32 v[16:17], v[98:99], v[8:9]
	s_waitcnt lgkmcnt(0)
	v_permlane16_swap_b32_e32 v20, v14
	v_add_f32_e32 v6, v14, v20
	v_mov_b32_e32 v7, v6
	v_cvt_pk_bf16_f32 v8, v10, v11
	v_cvt_pk_bf16_f32 v9, v12, v13
	v_cvt_pk_bf16_f32 v10, v18, v19
	v_cvt_pk_bf16_f32 v11, v16, v17
	global_store_dwordx4 v[50:51], v[8:11], off offset:256
	v_permlane32_swap_b32_e32 v7, v6
	s_and_saveexec_b64 s[10:11], s[0:1]
	s_cbranch_execz .LBB0_1461
	s_waitcnt lgkmcnt(0)
	v_add_f32_e32 v8, v6, v7
	s_lshl_b32 s38, s26, 2
	v_lshlrev_b64 v[6:7], 6, v[48:49]
	s_ashr_i32 s39, s38, 31
	v_lshl_add_u64 v[6:7], s[64:65], 0, v[6:7]
	v_lshl_add_u64 v[6:7], s[38:39], 2, v[6:7]
	s_lshl_b32 s18, s29, 2
	v_lshl_add_u64 v[6:7], v[6:7], 0, s[18:19]
	global_store_dword v[6:7], v8, off

.LBB0_1976:
	s_and_b64 vcc, exec, s[40:41]
	s_cbranch_vccnz .LBB0_1980
	v_mul_f32_e32 v14, v181, v181
	v_mul_f32_e32 v177, v177, v177
	v_fmac_f32_e32 v14, v180, v180
	v_mul_f32_e32 v180, v182, v182
	v_fmac_f32_e32 v177, v176, v176
	v_mul_f32_e32 v176, v178, v178
	v_fmac_f32_e32 v180, v183, v183
	v_fmac_f32_e32 v176, v179, v179
	v_add_f32_e32 v14, v14, v180
	v_add_f32_e32 v176, v177, v176
	v_add_f32_e32 v14, v14, v176
	v_mul_f32_e32 v176, v173, v173
	v_mul_f32_e32 v177, v174, v174
	v_fmac_f32_e32 v176, v172, v172
	v_fmac_f32_e32 v177, v175, v175
	v_add_f32_e32 v176, v176, v177
	v_add_f32_e32 v14, v14, v176
	v_mul_f32_e32 v176, v169, v169
	v_mul_f32_e32 v177, v170, v170
	v_fmac_f32_e32 v176, v168, v168
	v_fmac_f32_e32 v177, v171, v171
	v_add_f32_e32 v176, v176, v177
	v_add_f32_e32 v14, v176, v14
	v_mov_b32_e32 v180, v14
	v_pk_mul_f32 v[178:179], v[68:69], v[168:169]
	v_pk_mul_f32 v[172:173], v[72:73], v[172:173]
	v_pk_mul_f32 v[174:175], v[74:75], v[174:175]
	v_pk_mul_f32 v[176:177], v[70:71], v[170:171]
	s_waitcnt lgkmcnt(0)
	v_permlane16_swap_b32_e32 v180, v14
	v_add_f32_e32 v14, v14, v180
	v_mov_b32_e32 v168, v14
	v_cvt_pk_bf16_f32 v170, v172, v173
	v_cvt_pk_bf16_f32 v171, v174, v175
	v_cvt_pk_bf16_f32 v172, v178, v179
	v_cvt_pk_bf16_f32 v173, v176, v177
	global_store_dwordx4 v[210:211], v[170:173], off offset:256
	v_permlane32_swap_b32_e32 v168, v14
	s_and_saveexec_b64 s[10:11], s[0:1]
	s_cbranch_execz .LBB0_1979
	v_readlane_b32 s28, v251, 24
	s_waitcnt lgkmcnt(0)
	v_add_f32_e32 v14, v14, v168
	s_lshl_b32 s14, s93, 2
	v_lshlrev_b64 v[168:169], 6, v[204:205]
	v_readlane_b32 s29, v251, 25
	s_ashr_i32 s15, s14, 31
	s_lshl_b32 s18, s63, 2
	v_lshl_add_u64 v[168:169], s[28:29], 0, v[168:169]
	v_lshl_add_u64 v[168:169], s[14:15], 2, v[168:169]
	v_lshl_add_u64 v[168:169], v[168:169], 0, s[18:19]
	global_store_dword v[168:169], v14, off

.LBB0_1990:
	s_and_b64 vcc, exec, s[40:41]
	s_cbranch_vccnz .LBB0_1994
	v_mul_f32_e32 v14, v165, v165
	v_mul_f32_e32 v161, v161, v161
	v_fmac_f32_e32 v14, v164, v164
	v_mul_f32_e32 v164, v166, v166
	v_fmac_f32_e32 v161, v160, v160
	v_mul_f32_e32 v160, v162, v162
	v_fmac_f32_e32 v164, v167, v167
	v_fmac_f32_e32 v160, v163, v163
	v_add_f32_e32 v14, v14, v164
	v_add_f32_e32 v160, v161, v160
	v_add_f32_e32 v14, v14, v160
	v_mul_f32_e32 v160, v157, v157
	v_mul_f32_e32 v161, v158, v158
	v_fmac_f32_e32 v160, v156, v156
	v_fmac_f32_e32 v161, v159, v159
	v_add_f32_e32 v160, v160, v161
	v_add_f32_e32 v14, v14, v160
	v_mul_f32_e32 v160, v153, v153
	v_mul_f32_e32 v161, v154, v154
	v_fmac_f32_e32 v160, v152, v152
	v_fmac_f32_e32 v161, v155, v155
	v_add_f32_e32 v160, v160, v161
	v_add_f32_e32 v14, v160, v14
	v_mov_b32_e32 v164, v14
	v_pk_mul_f32 v[162:163], v[68:69], v[152:153]
	v_pk_mul_f32 v[156:157], v[72:73], v[156:157]
	v_pk_mul_f32 v[158:159], v[74:75], v[158:159]
	v_pk_mul_f32 v[160:161], v[70:71], v[154:155]
	s_waitcnt lgkmcnt(0)
	v_permlane16_swap_b32_e32 v164, v14
	v_add_f32_e32 v14, v14, v164
	v_mov_b32_e32 v152, v14
	v_cvt_pk_bf16_f32 v154, v156, v157
	v_cvt_pk_bf16_f32 v155, v158, v159
	v_cvt_pk_bf16_f32 v156, v162, v163
	v_cvt_pk_bf16_f32 v157, v160, v161
	global_store_dwordx4 v[208:209], v[154:157], off offset:256
	v_permlane32_swap_b32_e32 v152, v14
	s_and_saveexec_b64 s[10:11], s[0:1]
	s_cbranch_execz .LBB0_1993
	v_readlane_b32 s28, v251, 24
	s_waitcnt lgkmcnt(0)
	v_add_f32_e32 v14, v14, v152
	s_lshl_b32 s14, s93, 2
	v_lshlrev_b64 v[152:153], 6, v[206:207]
	v_readlane_b32 s29, v251, 25
	s_ashr_i32 s15, s14, 31
	s_lshl_b32 s18, s63, 2
	v_lshl_add_u64 v[152:153], s[28:29], 0, v[152:153]
	v_lshl_add_u64 v[152:153], s[14:15], 2, v[152:153]
	v_lshl_add_u64 v[152:153], v[152:153], 0, s[18:19]
	global_store_dword v[152:153], v14, off

.LBB0_2004:
	s_and_b64 vcc, exec, s[40:41]
	s_cbranch_vccnz .LBB0_2008
	v_mul_f32_e32 v14, v149, v149
	v_mul_f32_e32 v145, v145, v145
	v_fmac_f32_e32 v14, v148, v148
	v_mul_f32_e32 v148, v150, v150
	v_fmac_f32_e32 v145, v144, v144
	v_mul_f32_e32 v144, v146, v146
	v_fmac_f32_e32 v148, v151, v151
	v_fmac_f32_e32 v144, v147, v147
	v_add_f32_e32 v14, v14, v148
	v_add_f32_e32 v144, v145, v144
	v_add_f32_e32 v14, v14, v144
	v_mul_f32_e32 v144, v141, v141
	v_mul_f32_e32 v145, v142, v142
	v_fmac_f32_e32 v144, v140, v140
	v_fmac_f32_e32 v145, v143, v143
	v_add_f32_e32 v144, v144, v145
	v_add_f32_e32 v14, v14, v144
	v_mul_f32_e32 v144, v137, v137
	v_mul_f32_e32 v145, v138, v138
	v_fmac_f32_e32 v144, v136, v136
	v_fmac_f32_e32 v145, v139, v139
	v_add_f32_e32 v144, v144, v145
	v_add_f32_e32 v14, v144, v14
	v_mov_b32_e32 v148, v14
	v_pk_mul_f32 v[146:147], v[68:69], v[136:137]
	v_pk_mul_f32 v[140:141], v[72:73], v[140:141]
	v_pk_mul_f32 v[142:143], v[74:75], v[142:143]
	v_pk_mul_f32 v[144:145], v[70:71], v[138:139]
	s_waitcnt lgkmcnt(0)
	v_permlane16_swap_b32_e32 v148, v14
	v_add_f32_e32 v14, v14, v148
	v_mov_b32_e32 v136, v14
	v_cvt_pk_bf16_f32 v138, v140, v141
	v_cvt_pk_bf16_f32 v139, v142, v143
	v_cvt_pk_bf16_f32 v140, v146, v147
	v_cvt_pk_bf16_f32 v141, v144, v145
	global_store_dwordx4 v[178:179], v[138:141], off offset:256
	v_permlane32_swap_b32_e32 v136, v14
	s_and_saveexec_b64 s[10:11], s[0:1]
	s_cbranch_execz .LBB0_2007
	v_readlane_b32 s28, v251, 24
	s_waitcnt lgkmcnt(0)
	v_add_f32_e32 v14, v14, v136
	s_lshl_b32 s14, s93, 2
	v_lshlrev_b64 v[136:137], 6, v[176:177]
	v_readlane_b32 s29, v251, 25
	s_ashr_i32 s15, s14, 31
	s_lshl_b32 s18, s63, 2
	v_lshl_add_u64 v[136:137], s[28:29], 0, v[136:137]
	v_lshl_add_u64 v[136:137], s[14:15], 2, v[136:137]
	v_lshl_add_u64 v[136:137], v[136:137], 0, s[18:19]
	global_store_dword v[136:137], v14, off

.LBB0_2018:
	s_and_b64 vcc, exec, s[40:41]
	s_cbranch_vccnz .LBB0_2022
	v_mul_f32_e32 v14, v133, v133
	v_mul_f32_e32 v129, v129, v129
	v_fmac_f32_e32 v14, v132, v132
	v_mul_f32_e32 v132, v134, v134
	v_fmac_f32_e32 v129, v128, v128
	v_mul_f32_e32 v128, v130, v130
	v_fmac_f32_e32 v132, v135, v135
	v_fmac_f32_e32 v128, v131, v131
	v_add_f32_e32 v14, v14, v132
	v_add_f32_e32 v128, v129, v128
	v_add_f32_e32 v14, v14, v128
	v_mul_f32_e32 v128, v125, v125
	v_mul_f32_e32 v129, v126, v126
	v_fmac_f32_e32 v128, v124, v124
	v_fmac_f32_e32 v129, v127, v127
	v_add_f32_e32 v128, v128, v129
	v_add_f32_e32 v14, v14, v128
	v_mul_f32_e32 v128, v113, v113
	v_mul_f32_e32 v129, v114, v114
	v_fmac_f32_e32 v128, v112, v112
	v_fmac_f32_e32 v129, v115, v115
	v_add_f32_e32 v128, v128, v129
	v_add_f32_e32 v14, v128, v14
	v_mov_b32_e32 v130, v14
	v_pk_mul_f32 v[128:129], v[68:69], v[112:113]
	v_pk_mul_f32 v[126:127], v[74:75], v[126:127]
	v_pk_mul_f32 v[124:125], v[72:73], v[124:125]
	v_pk_mul_f32 v[114:115], v[70:71], v[114:115]
	s_waitcnt lgkmcnt(0)
	v_permlane16_swap_b32_e32 v130, v14
	v_add_f32_e32 v14, v14, v130
	v_mov_b32_e32 v112, v14
	v_cvt_pk_bf16_f32 v124, v124, v125
	v_cvt_pk_bf16_f32 v125, v126, v127
	v_cvt_pk_bf16_f32 v126, v128, v129
	v_cvt_pk_bf16_f32 v127, v114, v115
	global_store_dwordx4 v[162:163], v[124:127], off offset:256
	v_permlane32_swap_b32_e32 v112, v14
	s_and_saveexec_b64 s[10:11], s[0:1]
	s_cbranch_execz .LBB0_2021
	v_readlane_b32 s28, v251, 24
	s_waitcnt lgkmcnt(0)
	v_add_f32_e32 v14, v14, v112
	s_lshl_b32 s14, s93, 2
	v_lshlrev_b64 v[112:113], 6, v[160:161]
	v_readlane_b32 s29, v251, 25
	s_ashr_i32 s15, s14, 31
	s_lshl_b32 s18, s63, 2
	v_lshl_add_u64 v[112:113], s[28:29], 0, v[112:113]
	v_lshl_add_u64 v[112:113], s[14:15], 2, v[112:113]
	v_lshl_add_u64 v[112:113], v[112:113], 0, s[18:19]
	global_store_dword v[112:113], v14, off

.LBB0_2032:
	s_and_b64 vcc, exec, s[40:41]
	s_cbranch_vccnz .LBB0_2036
	v_mul_f32_e32 v14, v77, v77
	v_mul_f32_e32 v65, v65, v65
	v_fmac_f32_e32 v14, v76, v76
	v_mul_f32_e32 v76, v78, v78
	v_fmac_f32_e32 v65, v64, v64
	v_mul_f32_e32 v64, v66, v66
	v_fmac_f32_e32 v76, v79, v79
	v_fmac_f32_e32 v64, v67, v67
	v_add_f32_e32 v14, v14, v76
	v_add_f32_e32 v64, v65, v64
	v_add_f32_e32 v14, v14, v64
	v_mul_f32_e32 v64, v61, v61
	v_mul_f32_e32 v65, v62, v62
	v_fmac_f32_e32 v64, v60, v60
	v_fmac_f32_e32 v65, v63, v63
	v_add_f32_e32 v64, v64, v65
	v_add_f32_e32 v14, v14, v64
	v_mul_f32_e32 v64, v57, v57
	v_mul_f32_e32 v65, v58, v58
	v_fmac_f32_e32 v64, v56, v56
	v_fmac_f32_e32 v65, v59, v59
	v_add_f32_e32 v64, v64, v65
	v_add_f32_e32 v14, v64, v14
	v_mov_b32_e32 v76, v14
	v_pk_mul_f32 v[66:67], v[68:69], v[56:57]
	v_pk_mul_f32 v[60:61], v[72:73], v[60:61]
	v_pk_mul_f32 v[62:63], v[74:75], v[62:63]
	v_pk_mul_f32 v[64:65], v[70:71], v[58:59]
	s_waitcnt lgkmcnt(0)
	v_permlane16_swap_b32_e32 v76, v14
	v_add_f32_e32 v14, v14, v76
	v_mov_b32_e32 v56, v14
	v_cvt_pk_bf16_f32 v58, v60, v61
	v_cvt_pk_bf16_f32 v59, v62, v63
	v_cvt_pk_bf16_f32 v60, v66, v67
	v_cvt_pk_bf16_f32 v61, v64, v65
	global_store_dwordx4 v[146:147], v[58:61], off offset:256
	v_permlane32_swap_b32_e32 v56, v14
	s_and_saveexec_b64 s[10:11], s[0:1]
	s_cbranch_execz .LBB0_2035
	v_readlane_b32 s28, v251, 24
	s_waitcnt lgkmcnt(0)
	v_add_f32_e32 v14, v14, v56
	s_lshl_b32 s14, s93, 2
	v_lshlrev_b64 v[56:57], 6, v[144:145]
	v_readlane_b32 s29, v251, 25
	s_ashr_i32 s15, s14, 31
	s_lshl_b32 s18, s63, 2
	v_lshl_add_u64 v[56:57], s[28:29], 0, v[56:57]
	v_lshl_add_u64 v[56:57], s[14:15], 2, v[56:57]
	v_lshl_add_u64 v[56:57], v[56:57], 0, s[18:19]
	global_store_dword v[56:57], v14, off

.LBB0_2046:
	s_and_b64 vcc, exec, s[40:41]
	s_cbranch_vccnz .LBB0_2050
	v_mul_f32_e32 v14, v53, v53
	v_mul_f32_e32 v49, v49, v49
	v_fmac_f32_e32 v14, v52, v52
	v_mul_f32_e32 v52, v54, v54
	v_fmac_f32_e32 v49, v48, v48
	v_mul_f32_e32 v48, v50, v50
	v_fmac_f32_e32 v52, v55, v55
	v_fmac_f32_e32 v48, v51, v51
	v_add_f32_e32 v14, v14, v52
	v_add_f32_e32 v48, v49, v48
	v_add_f32_e32 v14, v14, v48
	v_mul_f32_e32 v48, v45, v45
	v_mul_f32_e32 v49, v46, v46
	v_fmac_f32_e32 v48, v44, v44
	v_fmac_f32_e32 v49, v47, v47
	v_add_f32_e32 v48, v48, v49
	v_add_f32_e32 v14, v14, v48
	v_mul_f32_e32 v48, v41, v41
	v_mul_f32_e32 v49, v42, v42
	v_fmac_f32_e32 v48, v40, v40
	v_fmac_f32_e32 v49, v43, v43
	v_add_f32_e32 v48, v48, v49
	v_add_f32_e32 v14, v48, v14
	v_mov_b32_e32 v52, v14
	v_pk_mul_f32 v[50:51], v[68:69], v[40:41]
	v_pk_mul_f32 v[44:45], v[72:73], v[44:45]
	v_pk_mul_f32 v[46:47], v[74:75], v[46:47]
	v_pk_mul_f32 v[48:49], v[70:71], v[42:43]
	s_waitcnt lgkmcnt(0)
	v_permlane16_swap_b32_e32 v52, v14
	v_add_f32_e32 v14, v14, v52
	v_mov_b32_e32 v40, v14
	v_cvt_pk_bf16_f32 v42, v44, v45
	v_cvt_pk_bf16_f32 v43, v46, v47
	v_cvt_pk_bf16_f32 v44, v50, v51
	v_cvt_pk_bf16_f32 v45, v48, v49
	global_store_dwordx4 v[130:131], v[42:45], off offset:256
	v_permlane32_swap_b32_e32 v40, v14
	s_and_saveexec_b64 s[10:11], s[0:1]
	s_cbranch_execz .LBB0_2049
	v_readlane_b32 s28, v251, 24
	s_waitcnt lgkmcnt(0)
	v_add_f32_e32 v14, v14, v40
	s_lshl_b32 s14, s93, 2
	v_lshlrev_b64 v[40:41], 6, v[128:129]
	v_readlane_b32 s29, v251, 25
	s_ashr_i32 s15, s14, 31
	s_lshl_b32 s18, s63, 2
	v_lshl_add_u64 v[40:41], s[28:29], 0, v[40:41]
	v_lshl_add_u64 v[40:41], s[14:15], 2, v[40:41]
	v_lshl_add_u64 v[40:41], v[40:41], 0, s[18:19]
	global_store_dword v[40:41], v14, off

.LBB0_2060:
	s_and_b64 vcc, exec, s[40:41]
	s_cbranch_vccnz .LBB0_2064
	v_mul_f32_e32 v14, v37, v37
	v_mul_f32_e32 v33, v33, v33
	v_fmac_f32_e32 v14, v36, v36
	v_mul_f32_e32 v36, v38, v38
	v_fmac_f32_e32 v33, v32, v32
	v_mul_f32_e32 v32, v34, v34
	v_fmac_f32_e32 v36, v39, v39
	v_fmac_f32_e32 v32, v35, v35
	v_add_f32_e32 v14, v14, v36
	v_add_f32_e32 v32, v33, v32
	v_add_f32_e32 v14, v14, v32
	v_mul_f32_e32 v32, v29, v29
	v_mul_f32_e32 v33, v30, v30
	v_fmac_f32_e32 v32, v28, v28
	v_fmac_f32_e32 v33, v31, v31
	v_add_f32_e32 v32, v32, v33
	v_add_f32_e32 v14, v14, v32
	v_mul_f32_e32 v32, v25, v25
	v_mul_f32_e32 v33, v26, v26
	v_fmac_f32_e32 v32, v24, v24
	v_fmac_f32_e32 v33, v27, v27
	v_add_f32_e32 v32, v32, v33
	v_add_f32_e32 v14, v32, v14
	v_mov_b32_e32 v36, v14
	v_pk_mul_f32 v[34:35], v[68:69], v[24:25]
	v_pk_mul_f32 v[28:29], v[72:73], v[28:29]
	v_pk_mul_f32 v[30:31], v[74:75], v[30:31]
	v_pk_mul_f32 v[32:33], v[70:71], v[26:27]
	s_waitcnt lgkmcnt(0)
	v_permlane16_swap_b32_e32 v36, v14
	v_add_f32_e32 v14, v14, v36
	v_mov_b32_e32 v24, v14
	v_cvt_pk_bf16_f32 v26, v28, v29
	v_cvt_pk_bf16_f32 v27, v30, v31
	v_cvt_pk_bf16_f32 v28, v34, v35
	v_cvt_pk_bf16_f32 v29, v32, v33
	global_store_dwordx4 v[66:67], v[26:29], off offset:256
	v_permlane32_swap_b32_e32 v24, v14
	s_and_saveexec_b64 s[10:11], s[0:1]
	s_cbranch_execz .LBB0_2063
	v_readlane_b32 s28, v251, 24
	s_waitcnt lgkmcnt(0)
	v_add_f32_e32 v14, v14, v24
	s_lshl_b32 s14, s93, 2
	v_lshlrev_b64 v[24:25], 6, v[64:65]
	v_readlane_b32 s29, v251, 25
	s_ashr_i32 s15, s14, 31
	s_lshl_b32 s18, s63, 2
	v_lshl_add_u64 v[24:25], s[28:29], 0, v[24:25]
	v_lshl_add_u64 v[24:25], s[14:15], 2, v[24:25]
	v_lshl_add_u64 v[24:25], v[24:25], 0, s[18:19]
	global_store_dword v[24:25], v14, off

.LBB0_2074:
	s_and_b64 vcc, exec, s[40:41]
	s_cbranch_vccnz .LBB0_2078
	v_mul_f32_e32 v14, v21, v21
	v_mul_f32_e32 v17, v17, v17
	v_fmac_f32_e32 v14, v20, v20
	v_mul_f32_e32 v20, v22, v22
	v_fmac_f32_e32 v17, v16, v16
	v_mul_f32_e32 v16, v18, v18
	v_fmac_f32_e32 v20, v23, v23
	v_fmac_f32_e32 v16, v19, v19
	v_add_f32_e32 v14, v14, v20
	v_add_f32_e32 v16, v17, v16
	v_add_f32_e32 v14, v14, v16
	v_mul_f32_e32 v16, v11, v11
	v_mul_f32_e32 v17, v12, v12
	v_fmac_f32_e32 v16, v10, v10
	v_fmac_f32_e32 v17, v13, v13
	v_add_f32_e32 v16, v16, v17
	v_add_f32_e32 v14, v14, v16
	v_mul_f32_e32 v16, v7, v7
	v_mul_f32_e32 v17, v8, v8
	v_fmac_f32_e32 v16, v6, v6
	v_fmac_f32_e32 v17, v9, v9
	v_add_f32_e32 v16, v16, v17
	v_add_f32_e32 v14, v16, v14
	v_mov_b32_e32 v20, v14
	v_pk_mul_f32 v[18:19], v[68:69], v[6:7]
	v_pk_mul_f32 v[10:11], v[72:73], v[10:11]
	v_pk_mul_f32 v[12:13], v[74:75], v[12:13]
	v_pk_mul_f32 v[16:17], v[70:71], v[8:9]
	s_waitcnt lgkmcnt(0)
	v_permlane16_swap_b32_e32 v20, v14
	v_add_f32_e32 v6, v14, v20
	v_mov_b32_e32 v7, v6
	v_cvt_pk_bf16_f32 v8, v10, v11
	v_cvt_pk_bf16_f32 v9, v12, v13
	v_cvt_pk_bf16_f32 v10, v18, v19
	v_cvt_pk_bf16_f32 v11, v16, v17
	global_store_dwordx4 v[50:51], v[8:11], off offset:256
	v_permlane32_swap_b32_e32 v7, v6
	s_and_saveexec_b64 s[10:11], s[0:1]
	s_cbranch_execz .LBB0_2077
	v_readlane_b32 s28, v251, 24
	s_waitcnt lgkmcnt(0)
	v_add_f32_e32 v8, v6, v7
	s_lshl_b32 s14, s93, 2
	v_lshlrev_b64 v[6:7], 6, v[48:49]
	v_readlane_b32 s29, v251, 25
	s_ashr_i32 s15, s14, 31
	s_lshl_b32 s18, s63, 2
	v_lshl_add_u64 v[6:7], s[28:29], 0, v[6:7]
	v_lshl_add_u64 v[6:7], s[14:15], 2, v[6:7]
	v_lshl_add_u64 v[6:7], v[6:7], 0, s[18:19]
	global_store_dword v[6:7], v8, off
